# FFN1 epilogue: second row-batch ssq loads issued right after the first wait (overlapping first-batch compute), no waits behind first-batch stores; on top of final combined
# speedup vs baseline: 1.0085x; 1.0085x over previous
; __device__ __forceinline__ float fast_sigmoid(float v) { return __builtin_amdgcn_rcpf(1.0f + __builtin_amdgcn_exp2f(-1.4426950408889634f * v)); }
; __device__ __forceinline__ u32x4 pack8(const float* v) { u32x4 w; w.x = cvt_pk_bf16(v[0], v[1]); w.y = cvt_pk_bf16(v[2], v[3]); w.z = cvt_pk_bf16(v[4], v[5]); w.w = cvt_pk_bf16(v[6], v[7]); return w; }
;     __device__ __forceinline__ void operator()(int row, int pn, int within, const float* a, const float* b, float) const { (void)apply(row, pn, within, a, b); }
;     __device__ __forceinline__ void operator()(int row, int pn, int within, const float* a, const float* b, float) const { Pre p = preload(row, pn, within, 0); finish(row, pn, within, a, b, p); }
; #define PG8_GATHER(ai, m) float a[8], b[8]; _Pragma("unroll") for (int j = 0; j < 4; ++j) { a[j] = acc[ai][0][m][0][j]; a[4 + j] = acc[ai][0][m][1][j]; b[j] = acc[ai][1][m][0][j]; b[4 + j] = acc[ai][1][m][1][j]; }
;     __device__ __forceinline__ void finish(int row, int pn, int within, const float* a, const float* b, const Pre& p) const {
;         const f32x4 s4 = p.s0 + p.s1; float sm = (s4[0] + s4[1]) + (s4[2] + s4[3]); sm += __shfl_xor(sm, 16); sm += __shfl_xor(sm, 32);
;         (*this)(row, pn, within, a, b, __builtin_amdgcn_rsqf(sm * (1.0f / DM) + EPS)); }
;     __device__ __forceinline__ void operator()(int row, int pn, int within, const float* a, const float* b, float rc) const {
;         float o[8];
; #pragma unroll
;         for (int j = 0; j < 8; ++j) { const float g = a[j] * rc, u = b[j] * rc; o[j] = g * fast_sigmoid(g) * u; }
;         *(u32x4*)(hidden + (size_t)row * DFF + pn * 128 + within) = pack8(o);
; template <class Epi> __device__ __forceinline__ void run_epi(const Epi& E, const f32x4 (&acc)[2][2][4][2], const Unit& u, int wr, int wc, int fr, int fq) {
;     ...
;     for (int ai = 0; ai < 2; ++ai) { const int row0 = u.pm * BM + ai * HALF + wr * 64 + fr; typename Epi::Pre pre[4];
; #pragma unroll
;         for (int m = 0; m < 4; ++m) pre[m] = E.preload(row0 + m * 16, u.pn, within, fq);
; #pragma unroll
;         for (int m = 0; m < 4; ++m) { PG8_GATHER(ai, m); E.finish(row0 + m * 16, u.pn, within, a, b, pre[m]); } }
.LBB0_599:
	s_lshl_b32 s17, s24, 8
	v_mov_b32_e32 v128, v165
	v_mov_b32_e32 v129, v164
	s_add_i32 s17, s17, s44
	s_lshl_b32 s24, s25, 7
	v_lshlrev_b32_e32 v158, 3, v128
	v_add_u32_e32 v154, s17, v129
	v_ashrrev_i32_e32 v159, 31, v158
	v_ashrrev_i32_e32 v155, 31, v154
	v_lshl_add_u64 v[156:157], v[158:159], 2, s[8:9]
	v_lshlrev_b64 v[128:129], 7, v[154:155]
	v_lshl_add_u64 v[132:133], v[156:157], 0, v[128:129]
	global_load_dwordx4 v[128:131], v[132:133], off
	s_nop 0
	global_load_dwordx4 v[132:135], v[132:133], off offset:16
	v_add_u32_e32 v160, 16, v154
	v_ashrrev_i32_e32 v161, 31, v160
	v_lshlrev_b64 v[152:153], 7, v[160:161]
	v_lshl_add_u64 v[152:153], v[156:157], 0, v[152:153]
	global_load_dwordx4 v[172:175], v[152:153], off
	global_load_dwordx4 v[176:179], v[152:153], off offset:16
	v_and_b32_e32 v159, 64, v170
	v_xor_b32_e32 v155, 16, v170
	v_add_u32_e32 v159, 64, v159
	v_xor_b32_e32 v161, 32, v170
	v_cmp_lt_i32_e32 vcc, v155, v159
	v_add_u32_e32 v162, 32, v154
	v_add_u32_e32 v188, s45, v158
	v_cndmask_b32_e32 v155, v170, v155, vcc
	v_cmp_lt_i32_e32 vcc, v161, v159
	v_add_u32_e32 v158, 48, v154
	v_ashrrev_i32_e32 v163, 31, v162
	v_cndmask_b32_e32 v159, v170, v161, vcc
	v_lshlrev_b32_e32 v161, 2, v155
	v_lshlrev_b32_e32 v155, 2, v159
	v_ashrrev_i32_e32 v159, 31, v158
	v_lshlrev_b64 v[180:181], 7, v[162:163]
	v_lshlrev_b64 v[182:183], 7, v[158:159]
	v_lshl_add_u64 v[184:185], v[156:157], 0, v[180:181]
	v_lshl_add_u64 v[190:191], v[156:157], 0, v[182:183]
	global_load_dwordx4 v[180:183], v[184:185], off
	s_nop 0
	global_load_dwordx4 v[184:187], v[184:185], off offset:16
	v_mov_b64_e32 v[152:153], s[10:11]
	s_ashr_i32 s25, s24, 31
	v_ashrrev_i32_e32 v189, 31, v188
	s_lshl_b64 s[24:25], s[24:25], 1
	s_andn2_b64 vcc, exec, s[0:1]
	s_mov_b64 s[0:1], -1
	s_waitcnt vmcnt(0)
	v_add_u32_e32 v192, 128, v154
	v_ashrrev_i32_e32 v193, 31, v192
	v_lshlrev_b64 v[192:193], 7, v[192:193]
	v_lshl_add_u64 v[192:193], v[156:157], 0, v[192:193]
	global_load_dwordx4 v[196:199], v[192:193], off
	global_load_dwordx4 v[200:203], v[192:193], off offset:16
	v_add_u32_e32 v192, 144, v154
	v_ashrrev_i32_e32 v193, 31, v192
	v_lshlrev_b64 v[192:193], 7, v[192:193]
	v_lshl_add_u64 v[192:193], v[156:157], 0, v[192:193]
	global_load_dwordx4 v[204:207], v[192:193], off
	global_load_dwordx4 v[208:211], v[192:193], off offset:16
	v_add_u32_e32 v192, 160, v154
	v_ashrrev_i32_e32 v193, 31, v192
	v_lshlrev_b64 v[192:193], 7, v[192:193]
	v_lshl_add_u64 v[192:193], v[156:157], 0, v[192:193]
	global_load_dwordx4 v[212:215], v[192:193], off
	global_load_dwordx4 v[216:219], v[192:193], off offset:16
	v_add_u32_e32 v192, 176, v154
	v_ashrrev_i32_e32 v193, 31, v192
	v_lshlrev_b64 v[192:193], 7, v[192:193]
	v_lshl_add_u64 v[192:193], v[156:157], 0, v[192:193]
	global_load_dwordx4 v[220:223], v[192:193], off
	global_load_dwordx4 v[224:227], v[192:193], off offset:16
	v_pk_add_f32 v[130:131], v[130:131], v[134:135]
	v_pk_add_f32 v[128:129], v[128:129], v[132:133]
	s_nop 0
	v_pk_mov_b32 v[132:133], v[128:129], v[130:131] op_sel:[1,0]
	v_mov_b32_e32 v129, v131
	v_pk_add_f32 v[128:129], v[132:133], v[128:129]
	v_pk_add_f32 v[130:131], v[172:173], v[176:177]
	v_add_f32_e32 v134, v128, v129
	ds_bpermute_b32 v135, v161, v134
	v_pk_add_f32 v[128:129], v[174:175], v[178:179]
	s_waitcnt lgkmcnt(0)
	v_add_f32_e32 v134, v134, v135
	ds_bpermute_b32 v135, v155, v134
	v_pk_mov_b32 v[132:133], v[130:131], v[128:129] op_sel:[1,0]
	v_mov_b32_e32 v131, v129
	v_pk_add_f32 v[128:129], v[132:133], v[130:131]
	s_nop 0
	v_add_f32_e32 v159, v128, v129
	s_waitcnt lgkmcnt(0)
	v_add_f32_e32 v128, v134, v135
	v_fmamk_f32 v128, v128, 0x3a000000, v171
	v_rsq_f32_e32 v172, v128
	ds_bpermute_b32 v163, v161, v159
	global_load_dwordx4 v[128:131], v[190:191], off
	global_load_dwordx4 v[132:135], v[190:191], off offset:16
	v_pk_mul_f32 v[126:127], v[126:127], v[172:173] op_sel_hi:[1,0]
	v_pk_mul_f32 v[120:121], v[120:121], v[172:173] op_sel_hi:[1,0]
	v_pk_mul_f32 v[122:123], v[122:123], v[172:173] op_sel_hi:[1,0]
	v_mul_f32_e32 v174, 0xbfb8aa3b, v126
	v_mul_f32_e32 v175, 0xbfb8aa3b, v127
	v_mul_f32_e32 v176, 0xbfb8aa3b, v120
	v_mul_f32_e32 v177, 0xbfb8aa3b, v121
	v_mul_f32_e32 v178, 0xbfb8aa3b, v122
	v_mul_f32_e32 v179, 0xbfb8aa3b, v123
	v_exp_f32_e32 v174, v174
	v_exp_f32_e32 v175, v175
	v_exp_f32_e32 v176, v176
	v_exp_f32_e32 v177, v177
	v_exp_f32_e32 v178, v178
	v_exp_f32_e32 v179, v179
	v_add_f32_e32 v174, 1.0, v174
	v_add_f32_e32 v175, 1.0, v175
	s_waitcnt lgkmcnt(0)
	v_add_f32_e32 v159, v159, v163
	v_add_f32_e32 v176, 1.0, v176
	v_add_f32_e32 v177, 1.0, v177
	v_add_f32_e32 v178, 1.0, v178
	v_add_f32_e32 v179, 1.0, v179
	v_rcp_f32_e32 v174, v174
	v_rcp_f32_e32 v175, v175
	ds_bpermute_b32 v163, v155, v159
	v_rcp_f32_e32 v176, v176
	v_rcp_f32_e32 v177, v177
	v_rcp_f32_e32 v178, v178
	v_rcp_f32_e32 v179, v179
	v_pk_mul_f32 v[124:125], v[124:125], v[172:173] op_sel_hi:[1,0]
	v_pk_mul_f32 v[116:117], v[116:117], v[172:173] op_sel_hi:[1,0]
	v_pk_mul_f32 v[118:119], v[118:119], v[172:173] op_sel_hi:[1,0]
	v_pk_mul_f32 v[112:113], v[112:113], v[172:173] op_sel_hi:[1,0]
	v_pk_mul_f32 v[114:115], v[114:115], v[172:173] op_sel_hi:[1,0]
	v_mul_f32_e32 v172, 0xbfb8aa3b, v124
	v_mul_f32_e32 v173, 0xbfb8aa3b, v125
	v_exp_f32_e32 v172, v172
	v_exp_f32_e32 v173, v173
	v_pk_mul_f32 v[126:127], v[126:127], v[174:175]
	v_pk_mul_f32 v[120:121], v[120:121], v[176:177]
	v_pk_mul_f32 v[122:123], v[122:123], v[178:179]
	v_pk_mul_f32 v[118:119], v[118:119], v[126:127]
	v_pk_mul_f32 v[112:113], v[112:113], v[120:121]
	v_pk_mul_f32 v[120:121], v[114:115], v[122:123]
	v_cvt_pk_bf16_f32 v115, v118, v119
	s_waitcnt lgkmcnt(0)
; __device__ __forceinline__ float fast_sigmoid(float v) { return __builtin_amdgcn_rcpf(1.0f + __builtin_amdgcn_exp2f(-1.4426950408889634f * v)); }
; __device__ __forceinline__ u32x4 pack8(const float* v) { u32x4 w; w.x = cvt_pk_bf16(v[0], v[1]); w.y = cvt_pk_bf16(v[2], v[3]); w.z = cvt_pk_bf16(v[4], v[5]); w.w = cvt_pk_bf16(v[6], v[7]); return w; }
;     __device__ __forceinline__ void operator()(int row, int pn, int within, const float* a, const float* b, float) const { (void)apply(row, pn, within, a, b); }
;     __device__ __forceinline__ void operator()(int row, int pn, int within, const float* a, const float* b, float) const { Pre p = preload(row, pn, within, 0); finish(row, pn, within, a, b, p); }
;     __device__ __forceinline__ void finish(int row, int pn, int within, const float* a, const float* b, const Pre& p) const {
;         const f32x4 s4 = p.s0 + p.s1; float sm = (s4[0] + s4[1]) + (s4[2] + s4[3]); sm += __shfl_xor(sm, 16); sm += __shfl_xor(sm, 32);
;         (*this)(row, pn, within, a, b, __builtin_amdgcn_rsqf(sm * (1.0f / DM) + EPS)); }
;     __device__ __forceinline__ void operator()(int row, int pn, int within, const float* a, const float* b, float rc) const {
;         float o[8];
; #pragma unroll
;         for (int j = 0; j < 8; ++j) { const float g = a[j] * rc, u = b[j] * rc; o[j] = g * fast_sigmoid(g) * u; }
;         *(u32x4*)(hidden + (size_t)row * DFF + pn * 128 + within) = pack8(o);
	v_add_f32_e32 v118, v159, v163
	v_fmamk_f32 v118, v118, 0x3a000000, v171
	v_add_f32_e32 v172, 1.0, v172
	v_add_f32_e32 v173, 1.0, v173
	v_rsq_f32_e32 v118, v118
	v_rcp_f32_e32 v172, v172
	v_rcp_f32_e32 v173, v173
	v_pk_mul_f32 v[108:109], v[108:109], v[118:119] op_sel_hi:[1,0]
	s_nop 0
	v_mul_f32_e32 v119, 0xbfb8aa3b, v108
	v_pk_mul_f32 v[124:125], v[124:125], v[172:173]
	v_exp_f32_e32 v119, v119
	v_pk_mul_f32 v[116:117], v[116:117], v[124:125]
	v_pk_mul_f32 v[110:111], v[110:111], v[118:119] op_sel_hi:[1,0]
	v_cvt_pk_bf16_f32 v114, v116, v117
	v_cvt_pk_bf16_f32 v116, v112, v113
	v_mad_i64_i32 v[112:113], s[26:27], v154, s52, v[152:153]
	v_cvt_pk_bf16_f32 v117, v120, v121
	v_lshl_add_u64 v[120:121], v[112:113], 0, s[24:25]
	v_lshlrev_b64 v[112:113], 1, v[188:189]
	v_lshl_add_u64 v[120:121], v[120:121], 0, v[112:113]
	global_store_dwordx4 v[120:121], v[114:117], off
	v_pk_mul_f32 v[100:101], v[100:101], v[118:119] op_sel_hi:[1,0]
	v_pk_mul_f32 v[102:103], v[102:103], v[118:119] op_sel_hi:[1,0]
	v_mul_f32_e32 v114, 0xbfb8aa3b, v109
	v_exp_f32_e32 v115, v114
	v_mul_f32_e32 v116, 0xbfb8aa3b, v110
	v_mul_f32_e32 v117, 0xbfb8aa3b, v111
	v_exp_f32_e32 v116, v116
	v_exp_f32_e32 v117, v117
	v_add_f32_e32 v114, 1.0, v119
	v_add_f32_e32 v115, 1.0, v115
	v_rcp_f32_e32 v114, v114
	v_rcp_f32_e32 v115, v115
	v_add_f32_e32 v116, 1.0, v116
	v_add_f32_e32 v117, 1.0, v117
	v_rcp_f32_e32 v116, v116
	v_rcp_f32_e32 v117, v117
	v_pk_mul_f32 v[108:109], v[108:109], v[114:115]
	v_pk_mul_f32 v[104:105], v[104:105], v[118:119] op_sel_hi:[1,0]
	v_pk_mul_f32 v[100:101], v[100:101], v[108:109]
	v_pk_mul_f32 v[108:109], v[110:111], v[116:117]
	v_mul_f32_e32 v110, 0xbfb8aa3b, v104
	v_pk_mul_f32 v[102:103], v[102:103], v[108:109]
	v_mul_f32_e32 v108, 0xbfb8aa3b, v105
	v_exp_f32_e32 v110, v110
	v_exp_f32_e32 v109, v108
	v_pk_mul_f32 v[106:107], v[106:107], v[118:119] op_sel_hi:[1,0]
	v_pk_add_f32 v[114:115], v[180:181], v[184:185]
	v_add_f32_e32 v108, 1.0, v110
	v_add_f32_e32 v109, 1.0, v109
	v_mul_f32_e32 v110, 0xbfb8aa3b, v106
	v_mul_f32_e32 v111, 0xbfb8aa3b, v107
	v_rcp_f32_e32 v108, v108
	v_rcp_f32_e32 v109, v109
	v_exp_f32_e32 v110, v110
	v_exp_f32_e32 v111, v111
	v_pk_mul_f32 v[96:97], v[96:97], v[118:119] op_sel_hi:[1,0]
	v_pk_mul_f32 v[104:105], v[104:105], v[108:109]
	v_add_f32_e32 v108, 1.0, v110
	v_add_f32_e32 v109, 1.0, v111
	v_pk_add_f32 v[110:111], v[182:183], v[186:187]
	v_rcp_f32_e32 v108, v108
	v_pk_mov_b32 v[116:117], v[114:115], v[110:111] op_sel:[1,0]
	v_mov_b32_e32 v115, v111
	v_pk_add_f32 v[110:111], v[116:117], v[114:115]
	v_rcp_f32_e32 v109, v109
	v_add_f32_e32 v110, v110, v111
	ds_bpermute_b32 v111, v161, v110
	v_pk_mul_f32 v[104:105], v[96:97], v[104:105]
	v_pk_mul_f32 v[96:97], v[98:99], v[118:119] op_sel_hi:[1,0]
	v_pk_mul_f32 v[98:99], v[106:107], v[108:109]
	s_waitcnt lgkmcnt(0)
	v_add_f32_e32 v108, v110, v111
	ds_bpermute_b32 v109, v155, v108
	v_pk_mul_f32 v[106:107], v[96:97], v[98:99]
	v_cvt_pk_bf16_f32 v96, v100, v101
	v_cvt_pk_bf16_f32 v97, v102, v103
	v_mad_i64_i32 v[102:103], s[26:27], v160, s52, v[152:153]
	s_waitcnt lgkmcnt(0)
	v_add_f32_e32 v100, v108, v109
	v_fmamk_f32 v100, v100, 0x3a000000, v171
	v_rsq_f32_e32 v100, v100
	v_lshl_add_u64 v[102:103], v[102:103], 0, s[24:25]
	v_cvt_pk_bf16_f32 v98, v104, v105
	v_cvt_pk_bf16_f32 v99, v106, v107
	v_pk_mul_f32 v[92:93], v[92:93], v[100:101] op_sel_hi:[1,0]
	v_lshl_add_u64 v[102:103], v[102:103], 0, v[112:113]
	v_mul_f32_e32 v101, 0xbfb8aa3b, v92
	v_exp_f32_e32 v101, v101
	global_store_dwordx4 v[102:103], v[96:99], off
	v_pk_mul_f32 v[94:95], v[94:95], v[100:101] op_sel_hi:[1,0]
	s_nop 0
	v_mul_f32_e32 v96, 0xbfb8aa3b, v93
	v_exp_f32_e32 v97, v96
	v_mul_f32_e32 v98, 0xbfb8aa3b, v94
	v_mul_f32_e32 v99, 0xbfb8aa3b, v95
	v_exp_f32_e32 v98, v98
	v_exp_f32_e32 v99, v99
	v_add_f32_e32 v96, 1.0, v101
	v_add_f32_e32 v97, 1.0, v97
	v_rcp_f32_e32 v96, v96
	v_rcp_f32_e32 v97, v97
	v_add_f32_e32 v98, 1.0, v98
	v_add_f32_e32 v99, 1.0, v99
	v_rcp_f32_e32 v98, v98
	v_rcp_f32_e32 v99, v99
	v_pk_mul_f32 v[84:85], v[84:85], v[100:101] op_sel_hi:[1,0]
	v_pk_mul_f32 v[92:93], v[92:93], v[96:97]
	v_pk_mul_f32 v[86:87], v[86:87], v[100:101] op_sel_hi:[1,0]
	v_pk_mul_f32 v[84:85], v[84:85], v[92:93]
	v_pk_mul_f32 v[92:93], v[94:95], v[98:99]
	v_pk_mul_f32 v[88:89], v[88:89], v[100:101] op_sel_hi:[1,0]
	v_pk_mul_f32 v[86:87], v[86:87], v[92:93]
	v_mul_f32_e32 v94, 0xbfb8aa3b, v88
	v_mul_f32_e32 v92, 0xbfb8aa3b, v89
	v_exp_f32_e32 v94, v94
	v_exp_f32_e32 v93, v92
	v_pk_mul_f32 v[90:91], v[90:91], v[100:101] op_sel_hi:[1,0]
	s_waitcnt vmcnt(2)
	v_pk_add_f32 v[96:97], v[128:129], v[132:133]
	v_add_f32_e32 v92, 1.0, v94
	v_add_f32_e32 v93, 1.0, v93
	v_mul_f32_e32 v94, 0xbfb8aa3b, v90
	v_mul_f32_e32 v95, 0xbfb8aa3b, v91
	v_rcp_f32_e32 v92, v92
	v_rcp_f32_e32 v93, v93
	v_exp_f32_e32 v94, v94
	v_exp_f32_e32 v95, v95
	v_pk_mul_f32 v[80:81], v[80:81], v[100:101] op_sel_hi:[1,0]
	v_pk_mul_f32 v[88:89], v[88:89], v[92:93]
	v_add_f32_e32 v92, 1.0, v94
	v_add_f32_e32 v93, 1.0, v95
	v_pk_add_f32 v[94:95], v[130:131], v[134:135]
	v_rcp_f32_e32 v92, v92
	v_pk_mov_b32 v[98:99], v[96:97], v[94:95] op_sel:[1,0]
	v_mov_b32_e32 v97, v95
	v_pk_add_f32 v[94:95], v[98:99], v[96:97]
	v_rcp_f32_e32 v93, v93
	v_add_f32_e32 v94, v94, v95
	ds_bpermute_b32 v95, v161, v94
	v_pk_mul_f32 v[88:89], v[80:81], v[88:89]
	v_pk_mul_f32 v[80:81], v[82:83], v[100:101] op_sel_hi:[1,0]
	v_pk_mul_f32 v[82:83], v[90:91], v[92:93]
	s_waitcnt lgkmcnt(0)
	v_add_f32_e32 v92, v94, v95
	ds_bpermute_b32 v93, v155, v92
	v_pk_mul_f32 v[90:91], v[80:81], v[82:83]
	v_cvt_pk_bf16_f32 v80, v84, v85
	v_cvt_pk_bf16_f32 v81, v86, v87
	v_mad_i64_i32 v[86:87], s[26:27], v162, s52, v[152:153]
	s_waitcnt lgkmcnt(0)
; __device__ __forceinline__ float fast_sigmoid(float v) { return __builtin_amdgcn_rcpf(1.0f + __builtin_amdgcn_exp2f(-1.4426950408889634f * v)); }
; __device__ __forceinline__ u32x4 pack8(const float* v) { u32x4 w; w.x = cvt_pk_bf16(v[0], v[1]); w.y = cvt_pk_bf16(v[2], v[3]); w.z = cvt_pk_bf16(v[4], v[5]); w.w = cvt_pk_bf16(v[6], v[7]); return w; }
;     __device__ __forceinline__ void operator()(int row, int pn, int within, const float* a, const float* b, float) const { (void)apply(row, pn, within, a, b); }
;     __device__ __forceinline__ void operator()(int row, int pn, int within, const float* a, const float* b, float) const { Pre p = preload(row, pn, within, 0); finish(row, pn, within, a, b, p); }
; #define PG8_GATHER(ai, m) float a[8], b[8]; _Pragma("unroll") for (int j = 0; j < 4; ++j) { a[j] = acc[ai][0][m][0][j]; a[4 + j] = acc[ai][0][m][1][j]; b[j] = acc[ai][1][m][0][j]; b[4 + j] = acc[ai][1][m][1][j]; }
;     __device__ __forceinline__ void finish(int row, int pn, int within, const float* a, const float* b, const Pre& p) const {
;         const f32x4 s4 = p.s0 + p.s1; float sm = (s4[0] + s4[1]) + (s4[2] + s4[3]); sm += __shfl_xor(sm, 16); sm += __shfl_xor(sm, 32);
;         (*this)(row, pn, within, a, b, __builtin_amdgcn_rsqf(sm * (1.0f / DM) + EPS)); }
;     __device__ __forceinline__ void operator()(int row, int pn, int within, const float* a, const float* b, float rc) const {
;         float o[8];
; #pragma unroll
;         for (int j = 0; j < 8; ++j) { const float g = a[j] * rc, u = b[j] * rc; o[j] = g * fast_sigmoid(g) * u; }
;         *(u32x4*)(hidden + (size_t)row * DFF + pn * 128 + within) = pack8(o);
; template <class Epi> __device__ __forceinline__ void run_epi(const Epi& E, const f32x4 (&acc)[2][2][4][2], const Unit& u, int wr, int wc, int fr, int fq) {
;     ...
;     for (int ai = 0; ai < 2; ++ai) { const int row0 = u.pm * BM + ai * HALF + wr * 64 + fr; typename Epi::Pre pre[4];
; #pragma unroll
;         for (int m = 0; m < 4; ++m) pre[m] = E.preload(row0 + m * 16, u.pn, within, fq);
; #pragma unroll
;         for (int m = 0; m < 4; ++m) { PG8_GATHER(ai, m); E.finish(row0 + m * 16, u.pn, within, a, b, pre[m]); } }
	v_add_f32_e32 v84, v92, v93
	v_fmamk_f32 v84, v84, 0x3a000000, v171
	v_rsq_f32_e32 v84, v84
	v_lshl_add_u64 v[86:87], v[86:87], 0, s[24:25]
	v_cvt_pk_bf16_f32 v82, v88, v89
	v_cvt_pk_bf16_f32 v83, v90, v91
	v_pk_mul_f32 v[76:77], v[76:77], v[84:85] op_sel_hi:[1,0]
	v_lshl_add_u64 v[86:87], v[86:87], 0, v[112:113]
	v_mul_f32_e32 v85, 0xbfb8aa3b, v76
	v_exp_f32_e32 v85, v85
	global_store_dwordx4 v[86:87], v[80:83], off
	v_add_u32_e32 v94, 0x80, v154
	v_ashrrev_i32_e32 v95, 31, v94
	v_mul_f32_e32 v80, 0xbfb8aa3b, v77
	v_pk_mul_f32 v[78:79], v[78:79], v[84:85] op_sel_hi:[1,0]
	v_exp_f32_e32 v81, v80
	v_mul_f32_e32 v82, 0xbfb8aa3b, v78
	v_mul_f32_e32 v83, 0xbfb8aa3b, v79
	v_exp_f32_e32 v82, v82
	v_exp_f32_e32 v83, v83
	v_add_f32_e32 v80, 1.0, v85
	v_add_f32_e32 v81, 1.0, v81
	v_rcp_f32_e32 v80, v80
	v_rcp_f32_e32 v81, v81
	v_add_f32_e32 v82, 1.0, v82
	v_add_f32_e32 v83, 1.0, v83
	v_rcp_f32_e32 v82, v82
	v_rcp_f32_e32 v83, v83
	v_pk_mul_f32 v[68:69], v[68:69], v[84:85] op_sel_hi:[1,0]
	v_pk_mul_f32 v[76:77], v[76:77], v[80:81]
	v_pk_mul_f32 v[72:73], v[72:73], v[84:85] op_sel_hi:[1,0]
	v_pk_mul_f32 v[68:69], v[68:69], v[76:77]
	v_pk_mul_f32 v[76:77], v[78:79], v[82:83]
	v_mul_f32_e32 v78, 0xbfb8aa3b, v72
	v_exp_f32_e32 v78, v78
	v_pk_mul_f32 v[70:71], v[70:71], v[84:85] op_sel_hi:[1,0]
	v_pk_mul_f32 v[74:75], v[74:75], v[84:85] op_sel_hi:[1,0]
	v_pk_mul_f32 v[70:71], v[70:71], v[76:77]
	v_mul_f32_e32 v76, 0xbfb8aa3b, v73
	v_exp_f32_e32 v77, v76
	v_add_f32_e32 v76, 1.0, v78
	v_mul_f32_e32 v78, 0xbfb8aa3b, v74
	v_mul_f32_e32 v79, 0xbfb8aa3b, v75
	v_exp_f32_e32 v78, v78
	v_exp_f32_e32 v79, v79
	v_add_f32_e32 v77, 1.0, v77
	v_rcp_f32_e32 v76, v76
	v_rcp_f32_e32 v77, v77
	v_add_f32_e32 v78, 1.0, v78
	v_add_f32_e32 v79, 1.0, v79
	v_rcp_f32_e32 v78, v78
	v_rcp_f32_e32 v79, v79
	v_pk_mul_f32 v[64:65], v[64:65], v[84:85] op_sel_hi:[1,0]
	v_pk_mul_f32 v[72:73], v[72:73], v[76:77]
	v_add_u32_e32 v76, 0x90, v154
	v_pk_mul_f32 v[72:73], v[64:65], v[72:73]
	v_pk_mul_f32 v[64:65], v[66:67], v[84:85] op_sel_hi:[1,0]
	v_pk_mul_f32 v[66:67], v[74:75], v[78:79]
	v_ashrrev_i32_e32 v77, 31, v76
	v_pk_mul_f32 v[74:75], v[64:65], v[66:67]
	v_cvt_pk_bf16_f32 v64, v68, v69
	v_mad_i64_i32 v[68:69], s[26:27], v158, s52, v[152:153]
	v_lshl_add_u64 v[68:69], v[68:69], 0, s[24:25]
	v_cvt_pk_bf16_f32 v65, v70, v71
	v_cvt_pk_bf16_f32 v66, v72, v73
	v_cvt_pk_bf16_f32 v67, v74, v75
	v_lshl_add_u64 v[68:69], v[68:69], 0, v[112:113]
	global_store_dwordx4 v[68:69], v[64:67], off
	v_lshlrev_b64 v[72:73], 7, v[76:77]
	v_lshl_add_u64 v[72:73], v[156:157], 0, v[72:73]
	v_lshlrev_b64 v[64:65], 7, v[94:95]
	v_lshl_add_u64 v[68:69], v[156:157], 0, v[64:65]
	v_mov_b64_e32 v[64:65], v[196:197]
	v_mov_b64_e32 v[66:67], v[198:199]
	s_nop 0
	v_mov_b64_e32 v[68:69], v[200:201]
	v_mov_b64_e32 v[70:71], v[202:203]
	s_nop 0
	v_mov_b64_e32 v[78:79], v[204:205]
	v_mov_b64_e32 v[80:81], v[206:207]
	v_mov_b64_e32 v[82:83], v[208:209]
	v_mov_b64_e32 v[84:85], v[210:211]
	v_add_u32_e32 v74, 0xa0, v154
	v_ashrrev_i32_e32 v75, 31, v74
	v_add_u32_e32 v72, 0xb0, v154
	v_ashrrev_i32_e32 v73, 31, v72
	v_pk_add_f32 v[66:67], v[66:67], v[70:71]
	v_pk_add_f32 v[64:65], v[64:65], v[68:69]
	v_pk_add_f32 v[78:79], v[78:79], v[82:83]
	v_pk_mov_b32 v[68:69], v[64:65], v[66:67] op_sel:[1,0]
	v_mov_b32_e32 v65, v67
	v_pk_add_f32 v[64:65], v[68:69], v[64:65]
	s_nop 0
	v_add_f32_e32 v66, v64, v65
	ds_bpermute_b32 v67, v161, v66
	v_lshlrev_b64 v[64:65], 7, v[74:75]
	v_lshl_add_u64 v[64:65], v[156:157], 0, v[64:65]
	v_mov_b64_e32 v[86:87], v[212:213]
	v_mov_b64_e32 v[88:89], v[214:215]
	v_mov_b64_e32 v[90:91], v[216:217]
	v_mov_b64_e32 v[92:93], v[218:219]
	s_waitcnt lgkmcnt(0)
	v_add_f32_e32 v66, v66, v67
	ds_bpermute_b32 v67, v155, v66
	s_waitcnt lgkmcnt(0)
	v_add_f32_e32 v64, v66, v67
	v_fmamk_f32 v64, v64, 0x3a000000, v171
	v_rsq_f32_e32 v96, v64
	v_lshlrev_b64 v[64:65], 7, v[72:73]
	v_lshl_add_u64 v[68:69], v[156:157], 0, v[64:65]
	v_pk_mul_f32 v[60:61], v[60:61], v[96:97] op_sel_hi:[1,0]
	s_nop 0
	v_mul_f32_e32 v64, 0xbfb8aa3b, v60
	v_exp_f32_e32 v73, v64
	v_mul_f32_e32 v75, 0xbfb8aa3b, v61
	v_exp_f32_e32 v75, v75
	v_pk_mul_f32 v[62:63], v[62:63], v[96:97] op_sel_hi:[1,0]
	v_add_f32_e32 v73, 1.0, v73
	v_rcp_f32_e32 v98, v73
	v_add_f32_e32 v73, 1.0, v75
	v_mul_f32_e32 v75, 0xbfb8aa3b, v62
	v_exp_f32_e32 v75, v75
	v_mul_f32_e32 v77, 0xbfb8aa3b, v63
	v_exp_f32_e32 v77, v77
	v_rcp_f32_e32 v99, v73
	v_add_f32_e32 v73, 1.0, v75
	v_rcp_f32_e32 v100, v73
	v_add_f32_e32 v73, 1.0, v77
	v_rcp_f32_e32 v101, v73
	v_pk_mul_f32 v[52:53], v[52:53], v[96:97] op_sel_hi:[1,0]
	v_pk_mul_f32 v[60:61], v[60:61], v[98:99]
	v_pk_mul_f32 v[54:55], v[54:55], v[96:97] op_sel_hi:[1,0]
	v_pk_mul_f32 v[52:53], v[52:53], v[60:61]
	v_pk_mul_f32 v[60:61], v[62:63], v[100:101]
	v_pk_mul_f32 v[56:57], v[56:57], v[96:97] op_sel_hi:[1,0]
	v_pk_mul_f32 v[54:55], v[54:55], v[60:61]
	v_mul_f32_e32 v62, 0xbfb8aa3b, v56
	v_mul_f32_e32 v60, 0xbfb8aa3b, v57
	v_exp_f32_e32 v62, v62
	v_exp_f32_e32 v61, v60
	v_pk_mul_f32 v[58:59], v[58:59], v[96:97] op_sel_hi:[1,0]
	v_pk_mul_f32 v[48:49], v[48:49], v[96:97] op_sel_hi:[1,0]
	v_add_f32_e32 v60, 1.0, v62
	v_add_f32_e32 v61, 1.0, v61
	v_mul_f32_e32 v62, 0xbfb8aa3b, v58
	v_mul_f32_e32 v63, 0xbfb8aa3b, v59
	v_rcp_f32_e32 v60, v60
	v_rcp_f32_e32 v61, v61
	v_exp_f32_e32 v62, v62
	v_exp_f32_e32 v63, v63
	v_mov_b64_e32 v[64:65], v[220:221]
	v_mov_b64_e32 v[66:67], v[222:223]
	s_nop 0
	v_mov_b64_e32 v[68:69], v[224:225]
	v_mov_b64_e32 v[70:71], v[226:227]
	v_pk_mul_f32 v[56:57], v[56:57], v[60:61]
	v_add_f32_e32 v60, 1.0, v62
	v_add_f32_e32 v61, 1.0, v63
	v_pk_add_f32 v[62:63], v[80:81], v[84:85]
	v_rcp_f32_e32 v60, v60
	v_pk_mov_b32 v[80:81], v[78:79], v[62:63] op_sel:[1,0]
	v_mov_b32_e32 v79, v63
	v_pk_add_f32 v[62:63], v[80:81], v[78:79]
	v_rcp_f32_e32 v61, v61
	v_add_f32_e32 v62, v62, v63
	ds_bpermute_b32 v63, v161, v62
	v_pk_mul_f32 v[56:57], v[48:49], v[56:57]
	v_pk_mul_f32 v[48:49], v[50:51], v[96:97] op_sel_hi:[1,0]
	v_pk_mul_f32 v[50:51], v[58:59], v[60:61]
	s_waitcnt lgkmcnt(0)
; __device__ __forceinline__ float fast_sigmoid(float v) { return __builtin_amdgcn_rcpf(1.0f + __builtin_amdgcn_exp2f(-1.4426950408889634f * v)); }
; __device__ __forceinline__ u32x4 pack8(const float* v) { u32x4 w; w.x = cvt_pk_bf16(v[0], v[1]); w.y = cvt_pk_bf16(v[2], v[3]); w.z = cvt_pk_bf16(v[4], v[5]); w.w = cvt_pk_bf16(v[6], v[7]); return w; }
;     __device__ __forceinline__ void operator()(int row, int pn, int within, const float* a, const float* b, float) const { (void)apply(row, pn, within, a, b); }
;     __device__ __forceinline__ void operator()(int row, int pn, int within, const float* a, const float* b, float) const { Pre p = preload(row, pn, within, 0); finish(row, pn, within, a, b, p); }
;     __device__ __forceinline__ void finish(int row, int pn, int within, const float* a, const float* b, const Pre& p) const {
;         const f32x4 s4 = p.s0 + p.s1; float sm = (s4[0] + s4[1]) + (s4[2] + s4[3]); sm += __shfl_xor(sm, 16); sm += __shfl_xor(sm, 32);
;         (*this)(row, pn, within, a, b, __builtin_amdgcn_rsqf(sm * (1.0f / DM) + EPS)); }
;     __device__ __forceinline__ void operator()(int row, int pn, int within, const float* a, const float* b, float rc) const {
;         float o[8];
; #pragma unroll
;         for (int j = 0; j < 8; ++j) { const float g = a[j] * rc, u = b[j] * rc; o[j] = g * fast_sigmoid(g) * u; }
;         *(u32x4*)(hidden + (size_t)row * DFF + pn * 128 + within) = pack8(o);
	v_add_f32_e32 v60, v62, v63
	ds_bpermute_b32 v61, v155, v60
	v_pk_mul_f32 v[58:59], v[48:49], v[50:51]
	v_cvt_pk_bf16_f32 v48, v52, v53
	v_cvt_pk_bf16_f32 v49, v54, v55
	v_mad_i64_i32 v[54:55], s[26:27], v94, s52, v[152:153]
	s_waitcnt lgkmcnt(0)
	v_add_f32_e32 v52, v60, v61
	v_fmamk_f32 v52, v52, 0x3a000000, v171
	v_rsq_f32_e32 v52, v52
	v_lshl_add_u64 v[54:55], v[54:55], 0, s[24:25]
	v_cvt_pk_bf16_f32 v50, v56, v57
	v_cvt_pk_bf16_f32 v51, v58, v59
	v_pk_mul_f32 v[44:45], v[44:45], v[52:53] op_sel_hi:[1,0]
	v_lshl_add_u64 v[54:55], v[54:55], 0, v[112:113]
	v_mul_f32_e32 v53, 0xbfb8aa3b, v44
	v_exp_f32_e32 v53, v53
	global_store_dwordx4 v[54:55], v[48:51], off
	v_pk_mul_f32 v[46:47], v[46:47], v[52:53] op_sel_hi:[1,0]
	s_nop 0
	v_mul_f32_e32 v48, 0xbfb8aa3b, v45
	v_exp_f32_e32 v49, v48
	v_mul_f32_e32 v50, 0xbfb8aa3b, v46
	v_mul_f32_e32 v51, 0xbfb8aa3b, v47
	v_exp_f32_e32 v50, v50
	v_exp_f32_e32 v51, v51
	v_add_f32_e32 v48, 1.0, v53
	v_add_f32_e32 v49, 1.0, v49
	v_rcp_f32_e32 v48, v48
	v_rcp_f32_e32 v49, v49
	v_add_f32_e32 v50, 1.0, v50
	v_add_f32_e32 v51, 1.0, v51
	v_rcp_f32_e32 v50, v50
	v_rcp_f32_e32 v51, v51
	v_pk_mul_f32 v[36:37], v[36:37], v[52:53] op_sel_hi:[1,0]
	v_pk_mul_f32 v[44:45], v[44:45], v[48:49]
	v_pk_mul_f32 v[38:39], v[38:39], v[52:53] op_sel_hi:[1,0]
	v_pk_mul_f32 v[36:37], v[36:37], v[44:45]
	v_pk_mul_f32 v[44:45], v[46:47], v[50:51]
	v_pk_mul_f32 v[40:41], v[40:41], v[52:53] op_sel_hi:[1,0]
	v_pk_mul_f32 v[38:39], v[38:39], v[44:45]
	v_mul_f32_e32 v46, 0xbfb8aa3b, v40
	v_mul_f32_e32 v44, 0xbfb8aa3b, v41
	v_exp_f32_e32 v46, v46
	v_exp_f32_e32 v45, v44
	v_pk_mul_f32 v[42:43], v[42:43], v[52:53] op_sel_hi:[1,0]
	v_pk_add_f32 v[48:49], v[86:87], v[90:91]
	v_add_f32_e32 v44, 1.0, v46
	v_add_f32_e32 v45, 1.0, v45
	v_mul_f32_e32 v46, 0xbfb8aa3b, v42
	v_mul_f32_e32 v47, 0xbfb8aa3b, v43
	v_rcp_f32_e32 v44, v44
	v_rcp_f32_e32 v45, v45
	v_exp_f32_e32 v46, v46
	v_exp_f32_e32 v47, v47
	v_pk_mul_f32 v[32:33], v[32:33], v[52:53] op_sel_hi:[1,0]
	v_pk_mul_f32 v[40:41], v[40:41], v[44:45]
	v_add_f32_e32 v44, 1.0, v46
	v_add_f32_e32 v45, 1.0, v47
	v_pk_add_f32 v[46:47], v[88:89], v[92:93]
	v_rcp_f32_e32 v44, v44
	v_pk_mov_b32 v[50:51], v[48:49], v[46:47] op_sel:[1,0]
	v_mov_b32_e32 v49, v47
	v_pk_add_f32 v[46:47], v[50:51], v[48:49]
	v_rcp_f32_e32 v45, v45
	v_add_f32_e32 v46, v46, v47
	ds_bpermute_b32 v47, v161, v46
	v_pk_mul_f32 v[40:41], v[32:33], v[40:41]
	v_pk_mul_f32 v[32:33], v[34:35], v[52:53] op_sel_hi:[1,0]
	v_pk_mul_f32 v[34:35], v[42:43], v[44:45]
	s_waitcnt lgkmcnt(0)
	v_add_f32_e32 v44, v46, v47
	ds_bpermute_b32 v45, v155, v44
	v_pk_mul_f32 v[42:43], v[32:33], v[34:35]
	v_cvt_pk_bf16_f32 v32, v36, v37
	v_cvt_pk_bf16_f32 v33, v38, v39
	v_mad_i64_i32 v[38:39], s[26:27], v76, s52, v[152:153]
	s_waitcnt lgkmcnt(0)
; __device__ __forceinline__ float fast_sigmoid(float v) { return __builtin_amdgcn_rcpf(1.0f + __builtin_amdgcn_exp2f(-1.4426950408889634f * v)); }
; __device__ __forceinline__ u32x4 pack8(const float* v) { u32x4 w; w.x = cvt_pk_bf16(v[0], v[1]); w.y = cvt_pk_bf16(v[2], v[3]); w.z = cvt_pk_bf16(v[4], v[5]); w.w = cvt_pk_bf16(v[6], v[7]); return w; }
;     __device__ __forceinline__ void operator()(int row, int pn, int within, const float* a, const float* b, float) const { (void)apply(row, pn, within, a, b); }
;     __device__ __forceinline__ void operator()(int row, int pn, int within, const float* a, const float* b, float) const { Pre p = preload(row, pn, within, 0); finish(row, pn, within, a, b, p); }
;     __device__ __forceinline__ void finish(int row, int pn, int within, const float* a, const float* b, const Pre& p) const {
;         const f32x4 s4 = p.s0 + p.s1; float sm = (s4[0] + s4[1]) + (s4[2] + s4[3]); sm += __shfl_xor(sm, 16); sm += __shfl_xor(sm, 32);
;         (*this)(row, pn, within, a, b, __builtin_amdgcn_rsqf(sm * (1.0f / DM) + EPS)); }
;     __device__ __forceinline__ void operator()(int row, int pn, int within, const float* a, const float* b, float rc) const {
;         float o[8];
; #pragma unroll
;         for (int j = 0; j < 8; ++j) { const float g = a[j] * rc, u = b[j] * rc; o[j] = g * fast_sigmoid(g) * u; }
;         *(u32x4*)(hidden + (size_t)row * DFF + pn * 128 + within) = pack8(o);
	v_add_f32_e32 v36, v44, v45
	v_fmamk_f32 v36, v36, 0x3a000000, v171
	v_rsq_f32_e32 v36, v36
	v_lshl_add_u64 v[38:39], v[38:39], 0, s[24:25]
	v_cvt_pk_bf16_f32 v34, v40, v41
	v_cvt_pk_bf16_f32 v35, v42, v43
	v_pk_mul_f32 v[28:29], v[28:29], v[36:37] op_sel_hi:[1,0]
	v_lshl_add_u64 v[38:39], v[38:39], 0, v[112:113]
	v_mul_f32_e32 v37, 0xbfb8aa3b, v28
	v_exp_f32_e32 v37, v37
	global_store_dwordx4 v[38:39], v[32:35], off
	v_pk_mul_f32 v[30:31], v[30:31], v[36:37] op_sel_hi:[1,0]
	s_nop 0
	v_mul_f32_e32 v32, 0xbfb8aa3b, v29
	v_exp_f32_e32 v33, v32
	v_mul_f32_e32 v34, 0xbfb8aa3b, v30
	v_mul_f32_e32 v35, 0xbfb8aa3b, v31
	v_exp_f32_e32 v34, v34
	v_exp_f32_e32 v35, v35
	v_add_f32_e32 v32, 1.0, v37
	v_add_f32_e32 v33, 1.0, v33
	v_rcp_f32_e32 v32, v32
	v_rcp_f32_e32 v33, v33
	v_add_f32_e32 v34, 1.0, v34
	v_add_f32_e32 v35, 1.0, v35
	v_rcp_f32_e32 v34, v34
	v_rcp_f32_e32 v35, v35
	v_pk_mul_f32 v[20:21], v[20:21], v[36:37] op_sel_hi:[1,0]
	v_pk_mul_f32 v[28:29], v[28:29], v[32:33]
	v_pk_mul_f32 v[22:23], v[22:23], v[36:37] op_sel_hi:[1,0]
	v_pk_mul_f32 v[20:21], v[20:21], v[28:29]
	v_pk_mul_f32 v[28:29], v[30:31], v[34:35]
	v_pk_mul_f32 v[24:25], v[24:25], v[36:37] op_sel_hi:[1,0]
	v_pk_mul_f32 v[22:23], v[22:23], v[28:29]
	v_mul_f32_e32 v30, 0xbfb8aa3b, v24
	v_mul_f32_e32 v28, 0xbfb8aa3b, v25
	v_exp_f32_e32 v30, v30
	v_exp_f32_e32 v29, v28
	v_pk_mul_f32 v[26:27], v[26:27], v[36:37] op_sel_hi:[1,0]
	v_pk_add_f32 v[32:33], v[64:65], v[68:69]
	v_add_f32_e32 v28, 1.0, v30
	v_add_f32_e32 v29, 1.0, v29
	v_mul_f32_e32 v30, 0xbfb8aa3b, v26
	v_mul_f32_e32 v31, 0xbfb8aa3b, v27
	v_rcp_f32_e32 v28, v28
	v_rcp_f32_e32 v29, v29
	v_exp_f32_e32 v30, v30
	v_exp_f32_e32 v31, v31
	v_pk_mul_f32 v[16:17], v[16:17], v[36:37] op_sel_hi:[1,0]
	v_pk_mul_f32 v[24:25], v[24:25], v[28:29]
	v_add_f32_e32 v28, 1.0, v30
	v_add_f32_e32 v29, 1.0, v31
	v_pk_add_f32 v[30:31], v[66:67], v[70:71]
	v_rcp_f32_e32 v28, v28
	v_pk_mov_b32 v[34:35], v[32:33], v[30:31] op_sel:[1,0]
	v_mov_b32_e32 v33, v31
	v_pk_add_f32 v[30:31], v[34:35], v[32:33]
	v_rcp_f32_e32 v29, v29
	v_add_f32_e32 v30, v30, v31
	ds_bpermute_b32 v31, v161, v30
	v_pk_mul_f32 v[24:25], v[16:17], v[24:25]
	v_pk_mul_f32 v[16:17], v[18:19], v[36:37] op_sel_hi:[1,0]
	v_pk_mul_f32 v[18:19], v[26:27], v[28:29]
	s_waitcnt lgkmcnt(0)
	v_add_f32_e32 v28, v30, v31
	ds_bpermute_b32 v29, v155, v28
	v_pk_mul_f32 v[26:27], v[16:17], v[18:19]
	v_cvt_pk_bf16_f32 v16, v20, v21
	v_cvt_pk_bf16_f32 v17, v22, v23
	v_mad_i64_i32 v[22:23], s[26:27], v74, s52, v[152:153]
	s_waitcnt lgkmcnt(0)
	v_add_f32_e32 v20, v28, v29
	v_fmamk_f32 v20, v20, 0x3a000000, v171
	v_rsq_f32_e32 v20, v20
	v_lshl_add_u64 v[22:23], v[22:23], 0, s[24:25]
	v_cvt_pk_bf16_f32 v18, v24, v25
	v_cvt_pk_bf16_f32 v19, v26, v27
	v_pk_mul_f32 v[12:13], v[12:13], v[20:21] op_sel_hi:[1,0]
	v_lshl_add_u64 v[22:23], v[22:23], 0, v[112:113]
	v_mul_f32_e32 v21, 0xbfb8aa3b, v12
	v_exp_f32_e32 v21, v21
	global_store_dwordx4 v[22:23], v[16:19], off
	v_pk_mul_f32 v[14:15], v[14:15], v[20:21] op_sel_hi:[1,0]
	s_nop 0
	v_mul_f32_e32 v16, 0xbfb8aa3b, v13
	v_exp_f32_e32 v17, v16
	v_mul_f32_e32 v18, 0xbfb8aa3b, v14
	v_mul_f32_e32 v19, 0xbfb8aa3b, v15
	v_exp_f32_e32 v18, v18
	v_exp_f32_e32 v19, v19
	v_add_f32_e32 v16, 1.0, v21
	v_add_f32_e32 v17, 1.0, v17
	v_rcp_f32_e32 v16, v16
	v_rcp_f32_e32 v17, v17
	v_add_f32_e32 v18, 1.0, v18
	v_add_f32_e32 v19, 1.0, v19
	v_rcp_f32_e32 v18, v18
	v_rcp_f32_e32 v19, v19
	v_pk_mul_f32 v[4:5], v[4:5], v[20:21] op_sel_hi:[1,0]
	v_pk_mul_f32 v[12:13], v[12:13], v[16:17]
	v_pk_mul_f32 v[8:9], v[8:9], v[20:21] op_sel_hi:[1,0]
	v_pk_mul_f32 v[4:5], v[4:5], v[12:13]
	v_pk_mul_f32 v[12:13], v[14:15], v[18:19]
	v_mul_f32_e32 v14, 0xbfb8aa3b, v8
	v_exp_f32_e32 v14, v14
	v_pk_mul_f32 v[6:7], v[6:7], v[20:21] op_sel_hi:[1,0]
	v_pk_mul_f32 v[10:11], v[10:11], v[20:21] op_sel_hi:[1,0]
	v_pk_mul_f32 v[6:7], v[6:7], v[12:13]
	v_mul_f32_e32 v12, 0xbfb8aa3b, v9
	v_exp_f32_e32 v13, v12
	v_add_f32_e32 v12, 1.0, v14
	v_mul_f32_e32 v14, 0xbfb8aa3b, v10
	v_mul_f32_e32 v15, 0xbfb8aa3b, v11
	v_exp_f32_e32 v14, v14
	v_exp_f32_e32 v15, v15
	v_add_f32_e32 v13, 1.0, v13
	v_rcp_f32_e32 v12, v12
	v_rcp_f32_e32 v13, v13
	v_add_f32_e32 v14, 1.0, v14
	v_add_f32_e32 v15, 1.0, v15
	v_rcp_f32_e32 v14, v14
	v_rcp_f32_e32 v15, v15
	v_pk_mul_f32 v[0:1], v[0:1], v[20:21] op_sel_hi:[1,0]
	v_pk_mul_f32 v[8:9], v[8:9], v[12:13]
	s_nop 0
	v_pk_mul_f32 v[8:9], v[0:1], v[8:9]
	v_pk_mul_f32 v[0:1], v[2:3], v[20:21] op_sel_hi:[1,0]
	v_pk_mul_f32 v[2:3], v[10:11], v[14:15]
	s_nop 0
	v_pk_mul_f32 v[10:11], v[0:1], v[2:3]
	v_cvt_pk_bf16_f32 v0, v4, v5
	v_mad_i64_i32 v[4:5], s[26:27], v72, s52, v[152:153]
	v_lshl_add_u64 v[4:5], v[4:5], 0, s[24:25]
	v_cvt_pk_bf16_f32 v1, v6, v7
	v_cvt_pk_bf16_f32 v2, v8, v9
	v_cvt_pk_bf16_f32 v3, v10, v11
	v_lshl_add_u64 v[4:5], v[4:5], 0, v[112:113]
	global_store_dwordx4 v[4:5], v[0:3], off
	s_cbranch_vccnz .LBB0_592
	s_andn2_b64 vcc, exec, s[6:7]
	s_cbranch_vccnz .LBB0_591
	s_barrier
	s_branch .LBB0_591
